# latent attention prologue: all K/V chunk, Q/gate and cached-context loads issued together, single wait
# speedup vs baseline: 1.0099x; 1.0099x over previous
.LBB0_362:
	s_andn2_b64 vcc, exec, s[0:1]
	s_cbranch_vccnz .LBB0_478
	s_mov_b64 s[0:1], 0x697b000
	s_mov_b64 s[10:11], 0x9f7b000
	s_mov_b64 s[8:9], 0xb83b000
	s_waitcnt lgkmcnt(0)
	s_barrier
	v_mbcnt_lo_u32_b32 v24, -1, 0
	v_mbcnt_hi_u32_b32 v24, -1, v24
	v_readlane_b32 s6, v255, 10
	v_add_u32_e32 v25, s3, v24
	v_add_u32_e32 v30, 0x200, v25
	s_add_u32 s0, s28, s0
	v_min_i32_e32 v4, s6, v30
	s_addc_u32 s1, s29, s1
	v_ashrrev_i32_e32 v0, 3, v4
	v_readlane_b32 s7, v255, 12
	v_lshlrev_b32_e32 v4, 4, v4
	v_add_u32_e32 v29, 0x400, v25
	v_add_u32_e32 v2, s7, v0
	v_mov_b64_e32 v[0:1], s[0:1]
	v_mad_i64_i32 v[2:3], s[4:5], v2, s62, v[0:1]
	v_readlane_b32 s4, v255, 13
	s_lshl_b32 s68, s4, 1
	v_lshl_add_u64 v[2:3], v[2:3], 0, s[68:69]
	v_and_b32_e32 v198, 0x70, v4
	v_min_i32_e32 v4, s6, v29
	v_lshl_add_u64 v[22:23], v[2:3], 0, v[198:199]
	v_ashrrev_i32_e32 v2, 3, v4
	v_add_u32_e32 v2, s7, v2
	v_mad_i64_i32 v[2:3], s[4:5], v2, s62, v[0:1]
	v_lshlrev_b32_e32 v4, 4, v4
	v_add_u32_e32 v28, 0x600, v25
	v_lshl_add_u64 v[2:3], v[2:3], 0, s[68:69]
	v_and_b32_e32 v198, 0x70, v4
	v_min_i32_e32 v8, s6, v28
	v_lshl_add_u64 v[20:21], v[2:3], 0, v[198:199]
	v_ashrrev_i32_e32 v2, 3, v8
	v_add_u32_e32 v2, s7, v2
	v_mad_i64_i32 v[2:3], s[4:5], v2, s62, v[0:1]
	v_lshlrev_b32_e32 v8, 4, v8
	v_lshl_add_u64 v[2:3], v[2:3], 0, s[68:69]
	v_and_b32_e32 v198, 0x70, v8
	v_add_u32_e32 v26, 0x800, v25
	v_lshl_add_u64 v[18:19], v[2:3], 0, v[198:199]
	v_min_i32_e32 v2, s6, v26
	v_ashrrev_i32_e32 v3, 3, v2
	v_add_u32_e32 v3, s7, v3
	v_mad_i64_i32 v[0:1], s[4:5], v3, s62, v[0:1]
	v_lshlrev_b32_e32 v2, 4, v2
	v_lshl_add_u64 v[0:1], v[0:1], 0, s[68:69]
	v_and_b32_e32 v198, 0x70, v2
	v_lshl_add_u64 v[16:17], v[0:1], 0, v[198:199]
	v_min_i32_e32 v31, s6, v25
	v_ashrrev_i32_e32 v32, 3, v31
	v_lshlrev_b32_e32 v31, 4, v31
	v_and_b32_e32 v198, 0x70, v31
	v_add_u32_e32 v34, s7, v32
	v_mov_b64_e32 v[32:33], s[0:1]
	v_mad_i64_i32 v[32:33], s[4:5], v34, s62, v[32:33]
	v_lshl_add_u64 v[32:33], v[32:33], 0, s[68:69]
	v_lshl_add_u64 v[36:37], v[32:33], 0, v[198:199]
	global_load_dwordx4 v[202:205], v[36:37], off offset:1024
	global_load_dwordx4 v[206:209], v[36:37], off offset:1280
	global_load_dwordx4 v[210:213], v[22:23], off offset:1024
	global_load_dwordx4 v[214:217], v[22:23], off offset:1280
	global_load_dwordx4 v[218:221], v[20:21], off offset:1024
	global_load_dwordx4 v[222:225], v[20:21], off offset:1280
	global_load_dwordx4 v[226:229], v[18:19], off offset:1024
	global_load_dwordx4 v[230:233], v[18:19], off offset:1280
	global_load_dwordx4 v[234:237], v[16:17], off offset:1024
	global_load_dwordx4 v[242:245], v[16:17], off offset:1280
	v_and_b32_e32 v27, 7, v24
	v_lshlrev_b32_e32 v146, 4, v27
	s_movk_i32 s4, 0x1430
	v_ashrrev_i32_e32 v148, 3, v25
	v_mad_u32_u24 v27, v27, s4, v146
	v_ashrrev_i32_e32 v150, 3, v30
	v_ashrrev_i32_e32 v152, 3, v29
	v_ashrrev_i32_e32 v154, 3, v28
	v_lshl_add_u32 v147, v148, 1, v27
	v_lshl_add_u32 v157, v150, 1, v27
	v_lshl_add_u32 v158, v152, 1, v27
	v_lshl_add_u32 v159, v154, 1, v27
	v_and_b32_e32 v3, 0xffffffe0, v148
	v_readlane_b32 s4, v255, 27
	v_lshrrev_b32_e32 v0, 6, v25
	v_and_b32_e32 v2, 31, v24
	v_add_u32_e32 v4, s4, v3
	v_readlane_b32 s4, v255, 14
	v_bfe_u32 v5, v24, 5, 1
	s_lshl_b32 s68, s86, 9
	v_and_or_b32 v115, v0, 3, s4
	v_or_b32_e32 v0, v4, v2
	v_readlane_b32 s4, v255, 11
	v_lshlrev_b32_e32 v198, 7, v115
	v_readlane_b32 s36, v254, 0
	v_add_u32_e32 v128, s4, v0
	v_mov_b64_e32 v[0:1], s[0:1]
	v_mad_i64_i32 v[0:1], s[0:1], v128, s62, v[0:1]
	v_lshl_add_u64 v[6:7], v[0:1], 0, v[198:199]
	v_lshlrev_b32_e32 v0, 4, v5
	v_mov_b32_e32 v1, v199
	s_lshl_b64 s[88:89], s[68:69], 2
	v_readlane_b32 s42, v254, 6
	v_lshl_add_u64 v[8:9], v[6:7], 0, v[0:1]
	v_readlane_b32 s43, v254, 7
	s_add_u32 s90, s42, s88
	global_load_dwordx4 v[96:99], v[8:9], off
	global_load_dwordx4 v[100:103], v[8:9], off offset:32
	global_load_dwordx4 v[104:107], v[8:9], off offset:64
	global_load_dwordx4 v[108:111], v[8:9], off offset:96
	s_addc_u32 s91, s43, s89
	v_lshlrev_b32_e32 v8, 8, v115
	v_mov_b32_e32 v9, v199
	v_lshl_add_u64 v[8:9], s[90:91], 0, v[8:9]
	v_lshlrev_b32_e32 v198, 3, v5
	v_lshl_add_u64 v[8:9], v[8:9], 0, v[0:1]
	v_lshl_add_u64 v[6:7], v[6:7], 0, v[198:199]
	global_load_dwordx4 v[92:95], v[8:9], off
	global_load_dwordx4 v[88:91], v[8:9], off offset:32
	global_load_dwordx2 v[144:145], v[6:7], off offset:1536
	global_load_dwordx2 v[142:143], v[6:7], off offset:1552
	global_load_dwordx2 v[140:141], v[6:7], off offset:1568
	global_load_dwordx2 v[138:139], v[6:7], off offset:1584
	global_load_dwordx4 v[84:87], v[8:9], off offset:64
	global_load_dwordx4 v[80:83], v[8:9], off offset:96
	global_load_dwordx4 v[76:79], v[8:9], off offset:128
	global_load_dwordx4 v[72:75], v[8:9], off offset:160
	global_load_dwordx2 v[136:137], v[6:7], off offset:1600
	global_load_dwordx2 v[134:135], v[6:7], off offset:1616
	global_load_dwordx2 v[132:133], v[6:7], off offset:1632
	global_load_dwordx2 v[130:131], v[6:7], off offset:1648
	global_load_dwordx4 v[68:71], v[8:9], off offset:192
	global_load_dwordx4 v[64:67], v[8:9], off offset:224
	s_lshl_b32 s20, s86, 3
	v_readlane_b32 s40, v254, 4
	v_readlane_b32 s41, v254, 5
	v_or_b32_e32 v6, s20, v115
	v_mov_b32_e32 v7, v199
	v_lshl_add_u64 v[6:7], v[6:7], 2, s[40:41]
	global_load_dword v1, v[6:7], off
	v_readlane_b32 s0, v255, 7
	v_readlane_b32 s1, v255, 8
	v_readlane_b32 s37, v254, 1
	v_readlane_b32 s38, v254, 2
	v_readlane_b32 s39, v254, 3
	v_readlane_b32 s44, v254, 8
	v_readlane_b32 s45, v254, 9
	v_readlane_b32 s46, v254, 10
	v_readlane_b32 s47, v254, 11
	v_readlane_b32 s48, v254, 12
	v_readlane_b32 s49, v254, 13
	v_readlane_b32 s50, v254, 14
	v_readlane_b32 s51, v254, 15
	s_andn2_b64 vcc, exec, s[0:1]
	s_cbranch_vccnz .Llat_nocache
	v_lshlrev_b32_e32 v194, 5, v24
	v_readlane_b32 s6, v255, 16
	s_lshl_b32 s0, s86, 8
	v_readlane_b32 s1, v255, 15
	v_and_b32_e32 v194, 0xe0, v194
	v_mov_b32_e32 v195, v199
	v_readlane_b32 s7, v255, 17
	s_add_i32 s0, s1, s0
	s_ashr_i32 s1, s0, 31
	v_lshl_add_u64 v[238:239], s[6:7], 0, v[194:195]
	v_readlane_b32 s6, v255, 18
	v_readlane_b32 s7, v255, 19
	v_ashrrev_i32_e32 v149, 31, v148
	v_ashrrev_i32_e32 v151, 31, v150
	v_ashrrev_i32_e32 v153, 31, v152
	v_ashrrev_i32_e32 v155, 31, v154
	v_lshl_add_u64 v[200:201], s[6:7], 0, v[194:195]
	v_lshl_add_u64 v[194:195], s[0:1], 0, v[148:149]
	v_lshlrev_b64 v[194:195], 9, v[194:195]
	v_lshl_add_u64 v[112:113], v[238:239], 0, v[194:195]
	v_lshl_add_u64 v[116:117], v[200:201], 0, v[194:195]
	global_load_dwordx4 v[6:9], v[112:113], off offset:16
	global_load_dwordx4 v[10:13], v[112:113], off
	global_load_dwordx4 v[16:19], v[116:117], off offset:16
	global_load_dwordx4 v[20:23], v[116:117], off
	v_lshl_add_u64 v[194:195], s[0:1], 0, v[150:151]
	v_lshlrev_b64 v[194:195], 9, v[194:195]
	v_lshl_add_u64 v[112:113], v[238:239], 0, v[194:195]
	v_lshl_add_u64 v[116:117], v[200:201], 0, v[194:195]
	global_load_dwordx4 v[32:35], v[112:113], off offset:16
	global_load_dwordx4 v[36:39], v[112:113], off
	global_load_dwordx4 v[40:43], v[116:117], off offset:16
	global_load_dwordx4 v[44:47], v[116:117], off
	v_lshl_add_u64 v[194:195], s[0:1], 0, v[152:153]
	v_lshlrev_b64 v[194:195], 9, v[194:195]
	v_lshl_add_u64 v[112:113], v[238:239], 0, v[194:195]
	v_lshl_add_u64 v[116:117], v[200:201], 0, v[194:195]
	global_load_dwordx4 v[48:51], v[112:113], off offset:16
	global_load_dwordx4 v[52:55], v[112:113], off
	global_load_dwordx4 v[56:59], v[116:117], off offset:16
	global_load_dwordx4 v[60:63], v[116:117], off
	v_lshl_add_u64 v[194:195], s[0:1], 0, v[154:155]
	v_lshlrev_b64 v[194:195], 9, v[194:195]
	v_lshl_add_u64 v[112:113], v[238:239], 0, v[194:195]
	v_lshl_add_u64 v[116:117], v[200:201], 0, v[194:195]
	global_load_dwordx4 v[180:183], v[112:113], off offset:16
	global_load_dwordx4 v[184:187], v[112:113], off
	global_load_dwordx4 v[188:191], v[116:117], off offset:16
	global_load_dwordx4 v[192:195], v[116:117], off
	s_waitcnt vmcnt(37)
	s_branch .Llat_chunks
.Llat_nocache:
	s_waitcnt vmcnt(21)
.Llat_chunks:
	v_readlane_b32 s6, v255, 9
	v_ashrrev_i32_e32 v129, 3, v26
	v_lshl_add_u32 v14, v129, 1, v27
	v_cmp_gt_i32_e32 vcc, s6, v25
	s_and_saveexec_b64 s[4:5], vcc
	s_cbranch_execz .Llat_c0
	v_mad_u32_u24 v31, v148, s2, v146
	ds_write_b128 v31, v[202:205]
	ds_write_b16 v147, v206 offset:46080
	ds_write_b16_d16_hi v147, v206 offset:46728
	ds_write_b16 v147, v207 offset:47376
	ds_write_b16_d16_hi v147, v207 offset:48024
	ds_write_b16 v147, v208 offset:48672
	ds_write_b16_d16_hi v147, v208 offset:49320
	ds_write_b16 v147, v209 offset:49968
	ds_write_b16_d16_hi v147, v209 offset:50616
.Llat_c0:
	s_or_b64 exec, exec, s[4:5]
	v_cmp_gt_i32_e32 vcc, s6, v30
	s_and_saveexec_b64 s[4:5], vcc
	s_cbranch_execz .Llat_c1
	v_mad_u32_u24 v31, v150, s2, v146
	ds_write_b128 v31, v[210:213]
	ds_write_b16 v157, v214 offset:46080
	ds_write_b16_d16_hi v157, v214 offset:46728
	ds_write_b16 v157, v215 offset:47376
	ds_write_b16_d16_hi v157, v215 offset:48024
	ds_write_b16 v157, v216 offset:48672
	ds_write_b16_d16_hi v157, v216 offset:49320
	ds_write_b16 v157, v217 offset:49968
	ds_write_b16_d16_hi v157, v217 offset:50616
.Llat_c1:
	s_or_b64 exec, exec, s[4:5]
	v_cmp_gt_i32_e32 vcc, s6, v29
	s_and_saveexec_b64 s[4:5], vcc
	s_cbranch_execz .Llat_c2
	v_mad_u32_u24 v31, v152, s2, v146
	ds_write_b128 v31, v[218:221]
	ds_write_b16 v158, v222 offset:46080
	ds_write_b16_d16_hi v158, v222 offset:46728
	ds_write_b16 v158, v223 offset:47376
	ds_write_b16_d16_hi v158, v223 offset:48024
	ds_write_b16 v158, v224 offset:48672
	ds_write_b16_d16_hi v158, v224 offset:49320
	ds_write_b16 v158, v225 offset:49968
	ds_write_b16_d16_hi v158, v225 offset:50616
.Llat_c2:
	s_or_b64 exec, exec, s[4:5]
	v_cmp_gt_i32_e32 vcc, s6, v28
	s_and_saveexec_b64 s[4:5], vcc
	s_cbranch_execz .Llat_c3
	v_mad_u32_u24 v31, v154, s2, v146
	ds_write_b128 v31, v[226:229]
	ds_write_b16 v159, v230 offset:46080
	ds_write_b16_d16_hi v159, v230 offset:46728
	ds_write_b16 v159, v231 offset:47376
	ds_write_b16_d16_hi v159, v231 offset:48024
	ds_write_b16 v159, v232 offset:48672
	ds_write_b16_d16_hi v159, v232 offset:49320
	ds_write_b16 v159, v233 offset:49968
	ds_write_b16_d16_hi v159, v233 offset:50616
.Llat_c3:
	s_or_b64 exec, exec, s[4:5]
	v_cmp_gt_i32_e32 vcc, s6, v26
	s_and_saveexec_b64 s[4:5], vcc
	s_cbranch_execz .Llat_c4
	v_mad_u32_u24 v31, v129, s2, v146
	ds_write_b128 v31, v[234:237]
	ds_write_b16 v14, v242 offset:46080
	ds_write_b16_d16_hi v14, v242 offset:46728
	ds_write_b16 v14, v243 offset:47376
	ds_write_b16_d16_hi v14, v243 offset:48024
	ds_write_b16 v14, v244 offset:48672
	ds_write_b16_d16_hi v14, v244 offset:49320
	ds_write_b16 v14, v245 offset:49968
	ds_write_b16_d16_hi v14, v245 offset:50616
.Llat_c4:
	s_or_b64 exec, exec, s[4:5]
	v_readlane_b32 s0, v255, 7
	v_readlane_b32 s1, v255, 8
	s_waitcnt vmcnt(0)
	v_mov_b32_e32 v15, 0
	s_andn2_b64 vcc, exec, s[0:1]
	v_cndmask_b32_e64 v14, 0, 1, s[0:1]
	s_nop 0
	v_cmp_ne_u32_e64 s[4:5], 1, v14
	s_cbranch_vccnz .LBB0_375
	v_cvt_pk_bf16_f32 v114, v6, v7
	v_cvt_pk_bf16_f32 v112, v10, v11
	v_cvt_pk_bf16_f32 v113, v12, v13
	v_cvt_pk_bf16_f32 v149, v8, v9
	v_cvt_pk_bf16_f32 v163, v20, v21
	v_cvt_pk_bf16_f32 v162, v22, v23
	v_cvt_pk_bf16_f32 v161, v16, v17
	v_cvt_pk_bf16_f32 v160, v18, v19
	v_cvt_pk_bf16_f32 v118, v32, v33
	v_cvt_pk_bf16_f32 v116, v36, v37
	v_cvt_pk_bf16_f32 v117, v38, v39
	v_cvt_pk_bf16_f32 v164, v34, v35
	v_cvt_pk_bf16_f32 v168, v44, v45
	v_cvt_pk_bf16_f32 v167, v46, v47
	v_cvt_pk_bf16_f32 v166, v40, v41
	v_cvt_pk_bf16_f32 v165, v42, v43
	v_cvt_pk_bf16_f32 v122, v48, v49
	v_cvt_pk_bf16_f32 v120, v52, v53
	v_cvt_pk_bf16_f32 v121, v54, v55
	v_cvt_pk_bf16_f32 v153, v50, v51
	v_cvt_pk_bf16_f32 v172, v60, v61
	v_cvt_pk_bf16_f32 v171, v62, v63
	v_cvt_pk_bf16_f32 v170, v56, v57
	v_cvt_pk_bf16_f32 v169, v58, v59
	v_cvt_pk_bf16_f32 v126, v180, v181
	v_cvt_pk_bf16_f32 v124, v184, v185
	v_cvt_pk_bf16_f32 v125, v186, v187
	v_cvt_pk_bf16_f32 v174, v182, v183
	v_cvt_pk_bf16_f32 v178, v192, v193
	v_cvt_pk_bf16_f32 v177, v194, v195
	v_cvt_pk_bf16_f32 v176, v188, v189
	v_cvt_pk_bf16_f32 v175, v190, v191
	s_branch .LBB0_376
